# previous + retention scan state update: the four k^T LDS fragment reads of each step issued together ahead of the MFMAs
# baseline (speedup 1.0000x reference)
; #define MFMA(a, b, c) __builtin_amdgcn_mfma_f32_32x32x16_bf16((a), (b), (c), 0, 0, 0)
; DI bf16x8 pack8f(const float* v) { u32x4 w = {cvtpk(v[0], v[1]), cvtpk(v[2], v[3]), cvtpk(v[4], v[5]), cvtpk(v[6], v[7])}; return __builtin_bit_cast(bf16x8, w); }
; DI void unpack8(bf16x8 v, float* f) { u32x4 w = __builtin_bit_cast(u32x4, v); for (int i = 0; i < 4; ++i) { f[2 * i] = bflo(w[i]); f[2 * i + 1] = bfhi(w[i]); } }
; template <bool ML>
; DI void scan_block(const Params& p, int sitem, char* smem) {
;     ...
;     if (active) {
;       const float decay = wsm[320];
; #pragma unroll
;       for (int i = 0; i < 4; ++i)
; #pragma unroll
;         for (int r = 0; r < 16; ++r) C[i][r] *= decay;
; #pragma unroll
;       for (int s4 = 0; s4 < 4; ++s4) {
;         float vf[8];
;         unpack8(ld8(vTS + (w * 32 + l32) * LT + s4 * 16 + hi * 8), vf);
; #pragma unroll
;         for (int j = 0; j < 8; ++j) {
;           const int s = s4 * 16 + hi * 8 + j;
;           vf[j] *= wsm[192 + s];
;         }
;         const bf16x8 bfr = pack8f(vf);
; #pragma unroll
;         for (int i = 0; i < 4; ++i) C[i] = MFMA(ld8(kTS + (32 * i + l32) * LT + s4 * 16 + hi * 8), bfr, C[i]);
;       }
.LBB0_1460:
	v_add_u32_e32 v86, v198, v165
	ds_read_b128 v[66:69], v86 offset:53248
	ds_read_b128 v[70:73], v201 offset:768
	ds_read_b32 v64, v209
	ds_read_b128 v[74:77], v201 offset:784
	s_cmp_lg_u32 s62, 36
	s_waitcnt lgkmcnt(0)
	v_lshlrev_b32_e32 v78, 16, v66
	v_and_b32_e32 v79, 0xffff0000, v66
	v_lshlrev_b32_e32 v66, 16, v67
	v_and_b32_e32 v67, 0xffff0000, v67
	v_pk_mul_f32 v[78:79], v[70:71], v[78:79]
	v_pk_mul_f32 v[80:81], v[72:73], v[66:67]
	ds_read_b128 v[96:99], v240 offset:34816
	ds_read_b128 v[100:103], v241 offset:34816
	ds_read_b128 v[104:107], v240 offset:44032
	ds_read_b128 v[108:111], v240 offset:48640
	v_lshlrev_b32_e32 v66, 16, v68
	v_and_b32_e32 v67, 0xffff0000, v68
	v_pk_mul_f32 v[74:75], v[74:75], v[66:67]
	v_lshlrev_b32_e32 v66, 16, v69
	v_and_b32_e32 v67, 0xffff0000, v69
	v_pk_mul_f32 v[76:77], v[76:77], v[66:67]
	v_cvt_pk_bf16_f32 v68, v74, v75
	v_cvt_pk_bf16_f32 v69, v76, v77
	v_pk_mul_f32 v[62:63], v[62:63], v[64:65] op_sel_hi:[1,0]
	v_pk_mul_f32 v[60:61], v[60:61], v[64:65] op_sel_hi:[1,0]
	v_pk_mul_f32 v[58:59], v[58:59], v[64:65] op_sel_hi:[1,0]
	v_pk_mul_f32 v[56:57], v[56:57], v[64:65] op_sel_hi:[1,0]
	v_pk_mul_f32 v[54:55], v[54:55], v[64:65] op_sel_hi:[1,0]
	v_pk_mul_f32 v[52:53], v[52:53], v[64:65] op_sel_hi:[1,0]
	v_pk_mul_f32 v[50:51], v[50:51], v[64:65] op_sel_hi:[1,0]
	v_pk_mul_f32 v[48:49], v[48:49], v[64:65] op_sel_hi:[1,0]
	v_cvt_pk_bf16_f32 v66, v78, v79
	v_cvt_pk_bf16_f32 v67, v80, v81
	v_pk_mul_f32 v[46:47], v[46:47], v[64:65] op_sel_hi:[1,0]
	v_pk_mul_f32 v[44:45], v[44:45], v[64:65] op_sel_hi:[1,0]
	s_waitcnt lgkmcnt(3)
	v_mfma_f32_32x32x16_bf16 v[48:63], v[96:99], v[66:69], v[48:63]
	v_mul_f32_e64 v42, v42, v64
	v_mul_f32_e64 v43, v43, v64
	v_mul_f32_e64 v40, v40, v64
	v_mul_f32_e64 v41, v41, v64
	v_pk_mul_f32 v[38:39], v[38:39], v[64:65] op_sel_hi:[1,0]
	v_pk_mul_f32 v[36:37], v[36:37], v[64:65] op_sel_hi:[1,0]
	v_pk_mul_f32 v[34:35], v[34:35], v[64:65] op_sel_hi:[1,0]
	v_pk_mul_f32 v[32:33], v[32:33], v[64:65] op_sel_hi:[1,0]
	v_pk_mul_f32 v[30:31], v[30:31], v[64:65] op_sel_hi:[1,0]
	v_pk_mul_f32 v[28:29], v[28:29], v[64:65] op_sel_hi:[1,0]
	s_waitcnt lgkmcnt(2)
	v_mfma_f32_32x32x16_bf16 v[32:47], v[100:103], v[66:69], v[32:47]
	v_mul_f32_e64 v26, v26, v64
	v_mul_f32_e64 v27, v27, v64
	v_mul_f32_e64 v24, v24, v64
	v_mul_f32_e64 v25, v25, v64
	v_pk_mul_f32 v[22:23], v[22:23], v[64:65] op_sel_hi:[1,0]
	v_pk_mul_f32 v[20:21], v[20:21], v[64:65] op_sel_hi:[1,0]
	v_pk_mul_f32 v[18:19], v[18:19], v[64:65] op_sel_hi:[1,0]
	v_pk_mul_f32 v[16:17], v[16:17], v[64:65] op_sel_hi:[1,0]
	v_pk_mul_f32 v[14:15], v[14:15], v[64:65] op_sel_hi:[1,0]
	v_pk_mul_f32 v[12:13], v[12:13], v[64:65] op_sel_hi:[1,0]
	s_waitcnt lgkmcnt(1)
	v_mfma_f32_32x32x16_bf16 v[16:31], v[104:107], v[66:69], v[16:31]
	ds_read_b128 v[70:73], v86 offset:53280
	ds_read_b128 v[78:81], v201 offset:832
	ds_read_b128 v[112:115], v241 offset:34848
	ds_read_b128 v[116:119], v240 offset:44064
	ds_read_b128 v[120:123], v240 offset:34848
	ds_read_b128 v[124:127], v240 offset:48672
	v_mul_f32_e64 v10, v10, v64
	v_mul_f32_e64 v11, v11, v64
	v_pk_mul_f32 v[8:9], v[8:9], v[64:65] op_sel_hi:[1,0]
	v_pk_mul_f32 v[6:7], v[6:7], v[64:65] op_sel_hi:[1,0]
	v_pk_mul_f32 v[4:5], v[4:5], v[64:65] op_sel_hi:[1,0]
	v_pk_mul_f32 v[2:3], v[2:3], v[64:65] op_sel_hi:[1,0]
	v_pk_mul_f32 v[0:1], v[0:1], v[64:65] op_sel_hi:[1,0]
	s_waitcnt lgkmcnt(0)
	v_lshlrev_b32_e32 v64, 16, v70
	v_and_b32_e32 v65, 0xffff0000, v70
	s_waitcnt lgkmcnt(6)
; #define MFMA(a, b, c) __builtin_amdgcn_mfma_f32_32x32x16_bf16((a), (b), (c), 0, 0, 0)
; DI bf16x8 pack8f(const float* v) { u32x4 w = {cvtpk(v[0], v[1]), cvtpk(v[2], v[3]), cvtpk(v[4], v[5]), cvtpk(v[6], v[7])}; return __builtin_bit_cast(bf16x8, w); }
; DI void unpack8(bf16x8 v, float* f) { u32x4 w = __builtin_bit_cast(u32x4, v); for (int i = 0; i < 4; ++i) { f[2 * i] = bflo(w[i]); f[2 * i + 1] = bfhi(w[i]); } }
; template <bool ML>
; DI void scan_block(const Params& p, int sitem, char* smem) {
;     ...
; #pragma unroll
;       for (int s4 = 0; s4 < 4; ++s4) {
;         float vf[8];
;         unpack8(ld8(vTS + (w * 32 + l32) * LT + s4 * 16 + hi * 8), vf);
; #pragma unroll
;         for (int j = 0; j < 8; ++j) {
;           const int s = s4 * 16 + hi * 8 + j;
;           vf[j] *= wsm[192 + s];
;         }
;         const bf16x8 bfr = pack8f(vf);
; #pragma unroll
;         for (int i = 0; i < 4; ++i) C[i] = MFMA(ld8(kTS + (32 * i + l32) * LT + s4 * 16 + hi * 8), bfr, C[i]);
;       }
	v_mfma_f32_32x32x16_bf16 v[0:15], v[108:111], v[66:69], v[0:15]
	v_mul_f32_e64 v68, v78, v64
	v_mul_f32_e64 v69, v79, v65
	ds_read_b128 v[64:67], v201 offset:848
	v_lshlrev_b32_e32 v70, 16, v71
	v_and_b32_e32 v71, 0xffff0000, v71
	v_lshlrev_b32_e32 v74, 16, v72
	v_and_b32_e32 v75, 0xffff0000, v72
	v_pk_mul_f32 v[70:71], v[80:81], v[70:71]
	s_waitcnt lgkmcnt(0)
	v_pk_mul_f32 v[74:75], v[64:65], v[74:75]
	v_lshlrev_b32_e32 v64, 16, v73
	v_and_b32_e32 v65, 0xffff0000, v73
	v_pk_mul_f32 v[72:73], v[66:67], v[64:65]
	v_cvt_pk_bf16_f32 v64, v68, v69
	v_cvt_pk_bf16_f32 v65, v70, v71
	v_cvt_pk_bf16_f32 v66, v74, v75
	v_cvt_pk_bf16_f32 v67, v72, v73
	s_mov_b32 s42, s62
	s_waitcnt lgkmcnt(0)
	v_mfma_f32_32x32x16_bf16 v[32:47], v[112:115], v[64:67], v[32:47]
	s_waitcnt lgkmcnt(0)
	v_mfma_f32_32x32x16_bf16 v[16:31], v[116:119], v[64:67], v[16:31]
	ds_read_b128 v[72:75], v86 offset:53312
	ds_read_b128 v[76:79], v201 offset:896
	s_waitcnt lgkmcnt(4)
	v_mfma_f32_32x32x16_bf16 v[48:63], v[120:123], v[64:67], v[48:63]
	s_waitcnt lgkmcnt(0)
	v_mfma_f32_32x32x16_bf16 v[0:15], v[124:127], v[64:67], v[0:15]
	v_lshlrev_b32_e32 v64, 16, v72
	v_and_b32_e32 v65, 0xffff0000, v72
	v_lshlrev_b32_e32 v68, 16, v73
	v_and_b32_e32 v69, 0xffff0000, v73
	v_mul_f32_e64 v76, v76, v64
	v_mul_f32_e64 v77, v77, v65
	ds_read_b128 v[64:67], v201 offset:912
	v_pk_mul_f32 v[72:73], v[78:79], v[68:69]
	ds_read_b128 v[96:99], v240 offset:34880
	ds_read_b128 v[100:103], v241 offset:34880
	ds_read_b128 v[104:107], v240 offset:44096
	ds_read_b128 v[108:111], v240 offset:48704
	v_lshlrev_b32_e32 v78, 16, v74
	v_and_b32_e32 v79, 0xffff0000, v74
	s_waitcnt lgkmcnt(0)
	v_pk_mul_f32 v[78:79], v[64:65], v[78:79]
	v_lshlrev_b32_e32 v64, 16, v75
	v_and_b32_e32 v65, 0xffff0000, v75
	v_pk_mul_f32 v[74:75], v[66:67], v[64:65]
	v_cvt_pk_bf16_f32 v64, v76, v77
	v_cvt_pk_bf16_f32 v65, v72, v73
	v_cvt_pk_bf16_f32 v66, v78, v79
	v_cvt_pk_bf16_f32 v67, v74, v75
	s_nop 1
	s_waitcnt lgkmcnt(3)
	v_mfma_f32_32x32x16_bf16 v[48:63], v[96:99], v[64:67], v[48:63]
	s_waitcnt lgkmcnt(2)
	v_mfma_f32_32x32x16_bf16 v[32:47], v[100:103], v[64:67], v[32:47]
	s_waitcnt lgkmcnt(1)
	v_mfma_f32_32x32x16_bf16 v[16:31], v[104:107], v[64:67], v[16:31]
	ds_read_b128 v[72:75], v86 offset:53344
	ds_read_b128 v[76:79], v201 offset:960
	s_waitcnt lgkmcnt(0)
	v_mfma_f32_32x32x16_bf16 v[0:15], v[108:111], v[64:67], v[0:15]
	v_lshlrev_b32_e32 v64, 16, v72
	v_and_b32_e32 v65, 0xffff0000, v72
	v_lshlrev_b32_e32 v68, 16, v73
	v_and_b32_e32 v69, 0xffff0000, v73
	v_mul_f32_e64 v76, v76, v64
	v_mul_f32_e64 v77, v77, v65
	ds_read_b128 v[64:67], v201 offset:976
	v_pk_mul_f32 v[72:73], v[78:79], v[68:69]
	ds_read_b128 v[112:115], v240 offset:34912
	ds_read_b128 v[116:119], v241 offset:34912
	ds_read_b128 v[120:123], v240 offset:44128
	ds_read_b128 v[124:127], v240 offset:48736
	v_lshlrev_b32_e32 v78, 16, v74
	v_and_b32_e32 v79, 0xffff0000, v74
	s_waitcnt lgkmcnt(0)
	v_pk_mul_f32 v[78:79], v[64:65], v[78:79]
	v_lshlrev_b32_e32 v64, 16, v75
	v_and_b32_e32 v65, 0xffff0000, v75
	v_pk_mul_f32 v[74:75], v[66:67], v[64:65]
	v_cvt_pk_bf16_f32 v64, v76, v77
	v_cvt_pk_bf16_f32 v65, v72, v73
	v_cvt_pk_bf16_f32 v66, v78, v79
	v_cvt_pk_bf16_f32 v67, v74, v75
	s_nop 1
	s_waitcnt lgkmcnt(3)
	v_mfma_f32_32x32x16_bf16 v[48:63], v[112:115], v[64:67], v[48:63]
	s_waitcnt lgkmcnt(2)
	v_mfma_f32_32x32x16_bf16 v[32:47], v[116:119], v[64:67], v[32:47]
	s_waitcnt lgkmcnt(1)
	v_mfma_f32_32x32x16_bf16 v[16:31], v[120:123], v[64:67], v[16:31]
	s_waitcnt lgkmcnt(0)
	v_mfma_f32_32x32x16_bf16 v[0:15], v[124:127], v[64:67], v[0:15]
	s_cbranch_scc0 .LBB0_1537
